# q0 idle 52 WGs (round 4) convert last 1664 tiles of layer-0 weight list, q3 converts the rest
# speedup vs baseline: 1.0203x; 1.0007x over previous
.LBB0_139:
	s_barrier
	v_readlane_b32 s4, v239, 37
	v_readlane_b32 s5, v241, 0
	v_readlane_b32 s6, v241, 9
	s_cmp_lg_u32 s4, 0
	s_cbranch_scc1 .LBB0_140
	s_cmpk_lt_i32 s5, 0xcc
	s_cbranch_scc1 .LBB0_140
	s_cmpk_lg_i32 s6, 0x100
	s_cbranch_scc1 .LBB0_140
	s_add_i32 s56, s5, 0xffffff34
	s_mov_b32 s8, 0
	v_readlane_b32 s14, v239, 42
	v_readlane_b32 s15, v239, 43
	v_lshrrev_b32_e32 v117, 5, v178
	v_and_b32_e32 v168, 31, v178
	v_lshlrev_b32_e32 v116, 2, v168
	v_mul_u32_u24_e32 v16, 0x204, v117
	v_lshl_add_u32 v16, v116, 2, v16
	v_and_b32_e32 v168, 7, v178
	v_lshlrev_b32_e32 v120, 4, v168
	v_mul_u32_u24_e32 v17, 0x1020, v168
	v_lshrrev_b32_e32 v119, 3, v178
	v_lshl_add_u32 v17, v119, 2, v17
	s_add_i32 s4, s56, 4704
	s_mov_b32 s39, 0
	s_cmpk_lt_u32 s4, 0x6c0
	s_cbranch_scc0 .Ltrq0_t1_0
	s_lshr_b32 s5, s4, 5
	s_and_b32 s6, s4, 31
	v_readlane_b32 s28, v241, 11
	v_readlane_b32 s29, v241, 12
	s_mul_i32 s9, s8, 0x3430000
	s_movk_i32 s38, 0x6860
	s_mov_b32 s2, 0
	s_mul_i32 s3, s8, 0x1b00000
	s_movk_i32 s44, 0x1000
	s_mov_b32 s39, 1
	s_branch .Ltrq0_dec_0

.Ltrq0_nosc:
	v_mov_b32_e32 v168, v16
	ds_write2_b32 v168, v100, v101 offset1:1
	ds_write2_b32 v168, v102, v103 offset0:2 offset1:3
	v_add_u32_e32 v168, 8256, v16
	ds_write2_b32 v168, v104, v105 offset1:1
	ds_write2_b32 v168, v106, v107 offset0:2 offset1:3
	v_add_u32_e32 v168, 16512, v16
	ds_write2_b32 v168, v108, v109 offset1:1
	ds_write2_b32 v168, v110, v111 offset0:2 offset1:3
	v_add_u32_e32 v168, 24768, v16
	ds_write2_b32 v168, v112, v113 offset1:1
	ds_write2_b32 v168, v114, v115 offset0:2 offset1:3
	s_add_i32 s56, s56, 52
	s_cmpk_lt_u32 s56, 0x680
	s_cselect_b32 s7, 1, 0
	s_cbranch_scc0 .Ltrq0_nonext
	s_add_i32 s4, s56, 4704
	s_mov_b32 s39, 0
	s_cmpk_lt_u32 s4, 0x6c0
	s_cbranch_scc0 .Ltrq0_t1_1
	s_lshr_b32 s5, s4, 5
	s_and_b32 s6, s4, 31
	v_readlane_b32 s28, v241, 11
	v_readlane_b32 s29, v241, 12
	s_mul_i32 s9, s8, 0x3430000
	s_movk_i32 s38, 0x6860
	s_mov_b32 s2, 0
	s_mul_i32 s3, s8, 0x1b00000
	s_movk_i32 s44, 0x1000
	s_mov_b32 s39, 1
	s_branch .Ltrq0_dec_1

.Ltrq3a_nosc:
	v_mov_b32_e32 v168, v16
	ds_write2_b32 v168, v100, v101 offset1:1
	ds_write2_b32 v168, v102, v103 offset0:2 offset1:3
	v_add_u32_e32 v168, 8256, v16
	ds_write2_b32 v168, v104, v105 offset1:1
	ds_write2_b32 v168, v106, v107 offset0:2 offset1:3
	v_add_u32_e32 v168, 16512, v16
	ds_write2_b32 v168, v108, v109 offset1:1
	ds_write2_b32 v168, v110, v111 offset0:2 offset1:3
	v_add_u32_e32 v168, 24768, v16
	ds_write2_b32 v168, v112, v113 offset1:1
	ds_write2_b32 v168, v114, v115 offset0:2 offset1:3
	s_add_i32 s70, s70, 256
	s_cmpk_lt_u32 s70, 0xba0
	s_cselect_b32 s7, 1, 0
	s_cbranch_scc0 .Ltrq3a_nonext
	s_add_i32 s4, s70, 1728
	s_mov_b32 s39, 0
	s_cmpk_lt_u32 s4, 0x6c0
	s_cbranch_scc0 .Ltrq3a_t1_1
	s_lshr_b32 s5, s4, 5
	s_and_b32 s6, s4, 31
	v_readlane_b32 s28, v241, 11
	v_readlane_b32 s29, v241, 12
	s_mul_i32 s9, s8, 0x3430000
	s_movk_i32 s38, 0x6860
	s_mov_b32 s2, 0
	s_mul_i32 s3, s8, 0x1b00000
	s_movk_i32 s44, 0x1000
	s_mov_b32 s39, 1
	s_branch .Ltrq3a_dec_1

.Ltrq3b_nosc:
	v_mov_b32_e32 v168, v16
	ds_write2_b32 v168, v100, v101 offset1:1
	ds_write2_b32 v168, v102, v103 offset0:2 offset1:3
	v_add_u32_e32 v168, 8256, v16
	ds_write2_b32 v168, v104, v105 offset1:1
	ds_write2_b32 v168, v106, v107 offset0:2 offset1:3
	v_add_u32_e32 v168, 16512, v16
	ds_write2_b32 v168, v108, v109 offset1:1
	ds_write2_b32 v168, v110, v111 offset0:2 offset1:3
	v_add_u32_e32 v168, 24768, v16
	ds_write2_b32 v168, v112, v113 offset1:1
	ds_write2_b32 v168, v114, v115 offset0:2 offset1:3
	s_add_i32 s68, s68, 256
	s_cmpk_lt_u32 s68, 0xba0
	s_cselect_b32 s7, 1, 0
	s_cbranch_scc0 .Ltrq3b_nonext
	s_add_i32 s4, s68, 1728
	s_mov_b32 s39, 0
	s_cmpk_lt_u32 s4, 0x6c0
	s_cbranch_scc0 .Ltrq3b_t1_1
	s_lshr_b32 s5, s4, 5
	s_and_b32 s6, s4, 31
	v_readlane_b32 s28, v241, 11
	v_readlane_b32 s29, v241, 12
	s_mul_i32 s9, s8, 0x3430000
	s_movk_i32 s38, 0x6860
	s_mov_b32 s2, 0
	s_mul_i32 s3, s8, 0x1b00000
	s_movk_i32 s44, 0x1000
	s_mov_b32 s39, 1
	s_branch .Ltrq3b_dec_1
